# attention d=1 tasks: merge partials and gain loads issued at task start instead of in the task epilogue
# speedup vs baseline: 1.0020x; 1.0020x over previous
; __device__ __forceinline__ unsigned pk2(float lo, float hi) { return pg8::cvt_pk_bf16(lo, hi); }
; template <int MODE> ...
;     ...
;     {
;         const float lt0 = l + __shfl_xor(l, 32);
;         const size_t row = seqrow0 + (size_t)(q0 + r) * dil;
;         if (MODE == 0) {
; #pragma unroll
;             for (int dt = 0; dt < 2; ++dt)
; #pragma unroll
;                 for (int ii = 0; ii < 4; ++ii) { u32x2 w; w.x = pk2(o[dt][4 * ii], o[dt][4 * ii + 1]); w.y = pk2(o[dt][4 * ii + 2], o[dt][4 * ii + 3]);
;                     *(u32x2*)(Po + row * 512 + head * 64 + 32 * dt + 8 * ii + 4 * h) = w; }
;             if (h == 0) Lo[row * 8 + head] = lt0;
;         } else {
;             const float lt = lt0 + L4[row * 8 + head] + L16[row * 8 + head]; const float inv = 1.f / lt; float ss = 0.f;
; #pragma unroll
;             for (int dt = 0; dt < 2; ++dt)
; #pragma unroll
;                 for (int ii = 0; ii < 4; ++ii) { const size_t off = row * 512 + head * 64 + 32 * dt + 8 * ii + 4 * h;
;                     const u32x2 a = *(const u32x2*)(P4 + off), c = *(const u32x2*)(P16 + off);
;                     const float add[4] = {__uint_as_float(a.x << 16) + __uint_as_float(c.x << 16), __uint_as_float(a.x & 0xffff0000u) + __uint_as_float(c.x & 0xffff0000u),
;                                           __uint_as_float(a.y << 16) + __uint_as_float(c.y << 16), __uint_as_float(a.y & 0xffff0000u) + __uint_as_float(c.y & 0xffff0000u)};
; #pragma unroll
;                     for (int e = 0; e < 4; ++e) { const float v = (o[dt][4 * ii + e] + add[e]) * inv; o[dt][4 * ii + e] = v; ss += v * v; } }
;             ss += __shfl_xor(ss, 32);
;             const float rr = rsqrtf(ss * (1.f / 64.f) + EPS);
.LBB0_617:
	v_and_b32_e32 v33, 64, v135
	v_xor_b32_e32 v32, 32, v135
	v_add_u32_e32 v33, 64, v33
	v_cmp_lt_i32_e32 vcc, v32, v33
	s_nop 1
	v_cndmask_b32_e32 v32, v135, v32, vcc
	v_lshlrev_b32_e32 v38, 2, v32
	ds_bpermute_b32 v32, v38, v138
	s_waitcnt lgkmcnt(0)
	v_add_f32_e32 v36, v138, v32
	s_nop 1
	s_waitcnt vmcnt(0) lgkmcnt(0)
	v_permlane32_swap_b32_e32 v144, v146
	v_permlane32_swap_b32_e32 v145, v147
	v_permlane32_swap_b32_e32 v148, v150
	v_permlane32_swap_b32_e32 v149, v151
	v_permlane32_swap_b32_e32 v152, v154
	v_permlane32_swap_b32_e32 v153, v155
	v_permlane32_swap_b32_e32 v156, v158
	v_permlane32_swap_b32_e32 v157, v159
	v_permlane32_swap_b32_e32 v160, v162
	v_permlane32_swap_b32_e32 v161, v163
	v_permlane32_swap_b32_e32 v164, v166
	v_permlane32_swap_b32_e32 v165, v167
	v_permlane32_swap_b32_e32 v168, v170
	v_permlane32_swap_b32_e32 v169, v171
	v_permlane32_swap_b32_e32 v172, v174
	v_permlane32_swap_b32_e32 v173, v175
	v_add_f32_e32 v34, v177, v36
	v_add_f32_e32 v32, v184, v34
	v_div_scale_f32 v33, s[0:1], v32, v32, 1.0
	v_rcp_f32_e32 v34, v33
	s_mov_b32 s0, 0x800000
	v_fma_f32 v35, -v33, v34, 1.0
	v_fmac_f32_e32 v34, v35, v34
	v_div_scale_f32 v35, vcc, 1.0, v32, 1.0
	v_mul_f32_e32 v36, v35, v34
	v_fma_f32 v37, -v33, v36, v35
	v_fmac_f32_e32 v36, v37, v34
	v_fma_f32 v33, -v33, v36, v35
	v_div_fmas_f32 v33, v33, v34, v36
	v_lshlrev_b64 v[34:35], 9, v[106:107]
	v_or3_b32 v35, v35, 0, 0
	v_or3_b32 v34, v34, v98, s83
	v_lshlrev_b64 v[34:35], 1, v[34:35]
	v_lshl_add_u64 v[36:37], s[72:73], 0, v[34:35]
	v_lshl_add_u64 v[40:41], s[74:75], 0, v[34:35]
	v_mov_b32_e32 v36, v144
	v_mov_b32_e32 v37, v145
	v_div_fixup_f32 v32, v33, v32, 1.0
	v_mov_b32_e32 v40, v160
	v_mov_b32_e32 v41, v161
	s_waitcnt vmcnt(0) lgkmcnt(0)
	v_lshlrev_b32_e32 v33, 16, v36
	v_and_b32_e32 v36, 0xffff0000, v36
	v_lshlrev_b32_e32 v39, 16, v40
	v_add_f32_e32 v33, v39, v33
	v_and_b32_e32 v39, 0xffff0000, v40
	v_add_f32_e32 v36, v39, v36
	v_lshlrev_b32_e32 v39, 16, v37
	v_lshlrev_b32_e32 v40, 16, v41
	v_add_f32_e32 v39, v40, v39
	v_and_b32_e32 v40, 0xffff0000, v41
	v_and_b32_e32 v37, 0xffff0000, v37
	v_add_f32_e32 v37, v40, v37
	v_add_f32_e32 v17, v17, v36
	v_add_f32_e32 v19, v19, v37
	v_or_b32_e32 v36, 16, v34
	v_mov_b32_e32 v37, v35
	v_lshl_add_u64 v[40:41], s[72:73], 0, v[36:37]
	v_lshl_add_u64 v[36:37], s[74:75], 0, v[36:37]
	v_mov_b32_e32 v40, v146
	v_mov_b32_e32 v41, v147
	v_add_f32_e32 v16, v16, v33
	v_mov_b32_e32 v36, v162
	v_mov_b32_e32 v37, v163
	v_add_f32_e32 v18, v18, v39
	v_mul_f32_e32 v17, v32, v17
	v_mul_f32_e32 v16, v32, v16
	v_mul_f32_e32 v42, v17, v17
	v_fmac_f32_e32 v42, v16, v16
	v_mul_f32_e32 v18, v32, v18
	v_fmac_f32_e32 v42, v18, v18
	v_mul_f32_e32 v19, v32, v19
	v_fmac_f32_e32 v42, v19, v19
	s_waitcnt vmcnt(0) lgkmcnt(0)
	v_lshlrev_b32_e32 v33, 16, v40
	v_lshlrev_b32_e32 v39, 16, v36
	v_add_f32_e32 v33, v39, v33
	v_and_b32_e32 v36, 0xffff0000, v36
	v_and_b32_e32 v39, 0xffff0000, v40
	v_add_f32_e32 v36, v36, v39
	v_lshlrev_b32_e32 v39, 16, v41
	v_lshlrev_b32_e32 v40, 16, v37
	v_add_f32_e32 v39, v40, v39
	v_and_b32_e32 v37, 0xffff0000, v37
	v_and_b32_e32 v40, 0xffff0000, v41
	v_add_f32_e32 v37, v37, v40
	v_add_f32_e32 v21, v21, v36
	v_add_f32_e32 v23, v23, v37
	v_or_b32_e32 v36, 32, v34
	v_mov_b32_e32 v37, v35
	v_lshl_add_u64 v[40:41], s[72:73], 0, v[36:37]
	v_lshl_add_u64 v[36:37], s[74:75], 0, v[36:37]
	v_mov_b32_e32 v40, v148
	v_mov_b32_e32 v41, v149
	v_add_f32_e32 v20, v20, v33
	v_mov_b32_e32 v36, v164
	v_mov_b32_e32 v37, v165
	v_add_f32_e32 v22, v22, v39
	v_mul_f32_e32 v20, v32, v20
	v_fmac_f32_e32 v42, v20, v20
	v_mul_f32_e32 v21, v32, v21
	v_fmac_f32_e32 v42, v21, v21
	v_mul_f32_e32 v22, v32, v22
	v_fmac_f32_e32 v42, v22, v22
	v_mul_f32_e32 v23, v32, v23
	v_fmac_f32_e32 v42, v23, v23
	s_waitcnt vmcnt(0) lgkmcnt(0)
	v_lshlrev_b32_e32 v33, 16, v40
	v_lshlrev_b32_e32 v39, 16, v36
	v_add_f32_e32 v33, v39, v33
	v_and_b32_e32 v36, 0xffff0000, v36
	v_and_b32_e32 v39, 0xffff0000, v40
	v_add_f32_e32 v39, v36, v39
	v_lshlrev_b32_e32 v36, 16, v41
	v_lshlrev_b32_e32 v40, 16, v37
	v_add_f32_e32 v40, v40, v36
	v_and_b32_e32 v36, 0xffff0000, v37
	v_and_b32_e32 v37, 0xffff0000, v41
	v_add_f32_e32 v24, v24, v33
	v_add_f32_e32 v37, v36, v37
	v_mul_f32_e32 v36, v32, v24
	v_add_f32_e32 v24, v25, v39
	v_mul_f32_e32 v33, v32, v24
	v_add_f32_e32 v24, v26, v40
	v_mul_f32_e32 v25, v32, v24
	v_add_f32_e32 v24, v27, v37
	v_or_b32_e32 v26, 48, v34
	v_mov_b32_e32 v27, v35
	v_lshl_add_u64 v[40:41], s[72:73], 0, v[26:27]
	v_lshl_add_u64 v[26:27], s[74:75], 0, v[26:27]
	v_mov_b32_e32 v40, v150
	v_mov_b32_e32 v41, v151
	v_fmac_f32_e32 v42, v36, v36
	v_mov_b32_e32 v26, v166
	v_mov_b32_e32 v27, v167
	v_fmac_f32_e32 v42, v33, v33
	v_fmac_f32_e32 v42, v25, v25
	v_mul_f32_e32 v24, v32, v24
	v_fmac_f32_e32 v42, v24, v24
	s_waitcnt vmcnt(0) lgkmcnt(0)
	v_lshlrev_b32_e32 v37, 16, v40
	v_lshlrev_b32_e32 v39, 16, v26
	v_add_f32_e32 v37, v39, v37
	v_and_b32_e32 v26, 0xffff0000, v26
	v_and_b32_e32 v39, 0xffff0000, v40
	v_add_f32_e32 v26, v26, v39
	v_lshlrev_b32_e32 v39, 16, v41
	v_lshlrev_b32_e32 v40, 16, v27
	v_add_f32_e32 v39, v40, v39
	v_and_b32_e32 v27, 0xffff0000, v27
	v_and_b32_e32 v40, 0xffff0000, v41
	v_add_f32_e32 v26, v29, v26
	v_add_f32_e32 v40, v27, v40
	v_add_f32_e32 v27, v28, v37
	v_mul_f32_e32 v28, v32, v26
	v_add_f32_e32 v26, v30, v39
	v_mul_f32_e32 v37, v32, v27
	v_mul_f32_e32 v27, v32, v26
	v_add_f32_e32 v26, v31, v40
	v_or_b32_e32 v30, 64, v34
	v_mov_b32_e32 v31, v35
	v_lshl_add_u64 v[40:41], s[72:73], 0, v[30:31]
	v_lshl_add_u64 v[30:31], s[74:75], 0, v[30:31]
	v_mov_b32_e32 v40, v152
	v_mov_b32_e32 v41, v153
	v_fmac_f32_e32 v42, v37, v37
	v_mov_b32_e32 v30, v168
	v_mov_b32_e32 v31, v169
	v_fmac_f32_e32 v42, v28, v28
	v_fmac_f32_e32 v42, v27, v27
	v_mul_f32_e32 v26, v32, v26
	v_fmac_f32_e32 v42, v26, v26
	s_waitcnt vmcnt(0) lgkmcnt(0)
; __device__ __forceinline__ unsigned pk2(float lo, float hi) { return pg8::cvt_pk_bf16(lo, hi); }
; template <int MODE> ...
;     ...
;             const float lt = lt0 + L4[row * 8 + head] + L16[row * 8 + head]; const float inv = 1.f / lt; float ss = 0.f;
; #pragma unroll
;             for (int dt = 0; dt < 2; ++dt)
; #pragma unroll
;                 for (int ii = 0; ii < 4; ++ii) { const size_t off = row * 512 + head * 64 + 32 * dt + 8 * ii + 4 * h;
;                     const u32x2 a = *(const u32x2*)(P4 + off), c = *(const u32x2*)(P16 + off);
;                     const float add[4] = {__uint_as_float(a.x << 16) + __uint_as_float(c.x << 16), __uint_as_float(a.x & 0xffff0000u) + __uint_as_float(c.x & 0xffff0000u),
;                                           __uint_as_float(a.y << 16) + __uint_as_float(c.y << 16), __uint_as_float(a.y & 0xffff0000u) + __uint_as_float(c.y & 0xffff0000u)};
; #pragma unroll
;                     for (int e = 0; e < 4; ++e) { const float v = (o[dt][4 * ii + e] + add[e]) * inv; o[dt][4 * ii + e] = v; ss += v * v; } }
;             ss += __shfl_xor(ss, 32);
;             const float rr = rsqrtf(ss * (1.f / 64.f) + EPS);
; #pragma unroll
;             for (int dt = 0; dt < 2; ++dt)
; #pragma unroll
;                 for (int ii = 0; ii < 4; ++ii) { const int d0 = head * 64 + 32 * dt + 8 * ii + 4 * h; const f32x4 gv = *(const f32x4*)(gain + d0);
;                     u32x2 w; w.x = pk2(o[dt][4 * ii] * rr * gv[0], o[dt][4 * ii + 1] * rr * gv[1]); w.y = pk2(o[dt][4 * ii + 2] * rr * gv[2], o[dt][4 * ii + 3] * rr * gv[3]);
	v_lshlrev_b32_e32 v29, 16, v40
	v_lshlrev_b32_e32 v39, 16, v30
	v_add_f32_e32 v29, v39, v29
	v_and_b32_e32 v30, 0xffff0000, v30
	v_and_b32_e32 v39, 0xffff0000, v40
	v_add_f32_e32 v30, v30, v39
	v_lshlrev_b32_e32 v39, 16, v41
	v_lshlrev_b32_e32 v40, 16, v31
	v_add_f32_e32 v40, v40, v39
	v_and_b32_e32 v31, 0xffff0000, v31
	v_and_b32_e32 v39, 0xffff0000, v41
	v_add_f32_e32 v0, v0, v29
	v_add_f32_e32 v41, v31, v39
	v_mul_f32_e32 v39, v32, v0
	v_add_f32_e32 v0, v1, v30
	v_mul_f32_e32 v31, v32, v0
	v_add_f32_e32 v0, v2, v40
	v_mul_f32_e32 v30, v32, v0
	v_add_f32_e32 v0, v3, v41
	v_mul_f32_e32 v29, v32, v0
	v_or_b32_e32 v0, 0x50, v34
	v_mov_b32_e32 v1, v35
	v_lshl_add_u64 v[2:3], s[72:73], 0, v[0:1]
	v_lshl_add_u64 v[0:1], s[74:75], 0, v[0:1]
	v_mov_b32_e32 v2, v154
	v_mov_b32_e32 v3, v155
	v_fmac_f32_e32 v42, v39, v39
	v_mov_b32_e32 v0, v170
	v_mov_b32_e32 v1, v171
	v_fmac_f32_e32 v42, v31, v31
	v_fmac_f32_e32 v42, v30, v30
	v_fmac_f32_e32 v42, v29, v29
	s_waitcnt vmcnt(0) lgkmcnt(0)
	v_lshlrev_b32_e32 v40, 16, v2
	v_and_b32_e32 v2, 0xffff0000, v2
	v_lshlrev_b32_e32 v41, 16, v0
	v_and_b32_e32 v0, 0xffff0000, v0
	v_add_f32_e32 v40, v41, v40
	v_add_f32_e32 v43, v0, v2
	v_lshlrev_b32_e32 v0, 16, v1
	v_lshlrev_b32_e32 v2, 16, v3
	v_and_b32_e32 v1, 0xffff0000, v1
	v_and_b32_e32 v3, 0xffff0000, v3
	v_add_f32_e32 v4, v4, v40
	v_pk_add_f32 v[0:1], v[2:3], v[0:1]
	v_mul_f32_e32 v41, v32, v4
	v_add_f32_e32 v4, v5, v43
	v_pk_add_f32 v[0:1], v[6:7], v[0:1]
	v_fmac_f32_e32 v42, v41, v41
	v_mul_f32_e32 v40, v32, v4
	v_pk_mul_f32 v[4:5], v[32:33], v[0:1] op_sel_hi:[0,1]
	v_fmac_f32_e32 v42, v40, v40
	v_pk_mul_f32 v[0:1], v[4:5], v[4:5]
	s_nop 0
	v_add_f32_e32 v0, v0, v42
	v_add_f32_e32 v44, v1, v0
	v_or_b32_e32 v0, 0x60, v34
	v_mov_b32_e32 v1, v35
	v_lshl_add_u64 v[2:3], s[72:73], 0, v[0:1]
	v_lshl_add_u64 v[0:1], s[74:75], 0, v[0:1]
	v_mov_b32_e32 v2, v156
	v_mov_b32_e32 v3, v157
	v_or_b32_e32 v34, 0x70, v34
	v_mov_b32_e32 v0, v172
	v_mov_b32_e32 v1, v173
	s_waitcnt vmcnt(0) lgkmcnt(0)
	v_lshlrev_b32_e32 v42, 16, v2
	v_and_b32_e32 v43, 0xffff0000, v2
	v_lshlrev_b32_e32 v6, 16, v0
	v_and_b32_e32 v7, 0xffff0000, v0
	v_pk_add_f32 v[6:7], v[42:43], v[6:7]
	v_lshlrev_b32_e32 v0, 16, v1
	v_pk_add_f32 v[6:7], v[8:9], v[6:7]
	v_lshlrev_b32_e32 v2, 16, v3
	v_and_b32_e32 v1, 0xffff0000, v1
	v_and_b32_e32 v3, 0xffff0000, v3
	v_pk_mul_f32 v[8:9], v[32:33], v[6:7] op_sel_hi:[0,1]
	v_pk_mul_f32 v[6:7], v[8:9], v[8:9]
	v_pk_add_f32 v[0:1], v[2:3], v[0:1]
	v_add_f32_e32 v6, v6, v44
	v_pk_add_f32 v[0:1], v[10:11], v[0:1]
	v_add_f32_e32 v42, v7, v6
	v_pk_mul_f32 v[6:7], v[32:33], v[0:1] op_sel_hi:[0,1]
	v_pk_mul_f32 v[0:1], v[6:7], v[6:7]
	v_lshl_add_u64 v[2:3], s[74:75], 0, v[34:35]
	v_add_f32_e32 v0, v0, v42
	v_add_f32_e32 v42, v1, v0
	v_lshl_add_u64 v[0:1], s[72:73], 0, v[34:35]
	v_mov_b32_e32 v0, v158
	v_mov_b32_e32 v1, v159
	s_nop 0
	v_mov_b32_e32 v2, v174
	v_mov_b32_e32 v3, v175
	s_waitcnt vmcnt(0) lgkmcnt(0)
	v_lshlrev_b32_e32 v34, 16, v0
	v_and_b32_e32 v35, 0xffff0000, v0
	v_lshlrev_b32_e32 v10, 16, v2
	v_and_b32_e32 v11, 0xffff0000, v2
	v_pk_add_f32 v[10:11], v[34:35], v[10:11]
	v_or_b32_e32 v35, s83, v98
	v_pk_add_f32 v[10:11], v[12:13], v[10:11]
	v_lshlrev_b32_e32 v34, 2, v35
	v_pk_mul_f32 v[10:11], v[32:33], v[10:11] op_sel_hi:[0,1]
	v_pk_mul_f32 v[12:13], v[10:11], v[10:11]
	v_lshlrev_b32_e32 v96, 1, v35
	v_add_f32_e32 v0, v12, v42
	v_add_f32_e32 v2, v13, v0
	v_and_b32_e32 v13, 0xffff0000, v1
	v_lshlrev_b32_e32 v12, 16, v1
	v_and_b32_e32 v1, 0xffff0000, v3
	v_lshlrev_b32_e32 v0, 16, v3
	v_pk_add_f32 v[0:1], v[12:13], v[0:1]
	s_nop 0
	v_pk_add_f32 v[0:1], v[14:15], v[0:1]
	s_nop 0
	v_pk_mul_f32 v[12:13], v[32:33], v[0:1] op_sel_hi:[0,1]
	v_pk_mul_f32 v[0:1], v[12:13], v[12:13]
	s_nop 0
	v_add_f32_e32 v0, v0, v2
	v_add_f32_e32 v0, v1, v0
	ds_bpermute_b32 v1, v38, v0
	s_waitcnt lgkmcnt(0)
	v_add_f32_e32 v0, v0, v1
	v_fmamk_f32 v0, v0, 0x3c800000, v133
	v_cmp_gt_f32_e32 vcc, s0, v0
	v_mul_f32_e32 v1, 0x4b800000, v0
	v_readlane_b32 s0, v235, 2
	v_cndmask_b32_e32 v0, v0, v1, vcc
	v_rsq_f32_e32 v0, v0
	v_readlane_b32 s1, v235, 3
	v_readlane_b32 s2, v235, 4
	v_readlane_b32 s3, v235, 5
	v_mul_f32_e32 v1, 0x45800000, v0
	v_cndmask_b32_e32 v32, v0, v1, vcc
	v_lshlrev_b64 v[0:1], 11, v[106:107]
	v_lshl_add_u64 v[14:15], s[0:1], 0, v[0:1]
	s_mov_b32 s1, s77
	v_readlane_b32 s76, v235, 14
	v_readlane_b32 s86, v235, 24
	v_readlane_b32 s87, v235, 25
	v_mul_f32_e32 v16, v16, v32
	v_mul_f32_e32 v8, v8, v32
	v_readlane_b32 s0, v235, 41
	v_readlane_b32 s77, v235, 15
	s_add_i32 s33, s33, s0
	v_mov_b32_e32 v0, v192
	v_mov_b32_e32 v1, v193
	v_mov_b32_e32 v2, v194
	v_mov_b32_e32 v3, v195
	s_mov_b32 s77, s1
	s_cmpk_gt_i32 s33, 0x1fff
	v_readlane_b32 s78, v235, 16
	v_readlane_b32 s79, v235, 17
	v_readlane_b32 s80, v235, 18
	v_readlane_b32 s81, v235, 19
	v_readlane_b32 s82, v235, 20
	v_readlane_b32 s83, v235, 21
	v_readlane_b32 s84, v235, 22
	v_readlane_b32 s85, v235, 23
	v_readlane_b32 s88, v235, 26
	v_readlane_b32 s89, v235, 27
	v_readlane_b32 s90, v235, 28
	v_readlane_b32 s91, v235, 29
	s_nop 0
	v_mul_f32_e32 v0, v0, v16
	v_mul_f32_e32 v16, v17, v32
	v_mul_f32_e32 v1, v1, v16
	v_cvt_pk_bf16_f32 v180, v0, v1
	v_mul_f32_e32 v0, v18, v32
	v_mul_f32_e32 v1, v19, v32
	v_mul_f32_e32 v0, v2, v0
	v_mul_f32_e32 v1, v3, v1
	v_cvt_pk_bf16_f32 v181, v0, v1
	v_lshl_add_u64 v[0:1], v[14:15], 0, v[96:97]
	s_nop 0
	v_mov_b32_e32 v14, v196
	v_mov_b32_e32 v15, v197
	v_mov_b32_e32 v16, v198
	v_mov_b32_e32 v17, v199
	v_mul_f32_e32 v2, v20, v32
	v_mul_f32_e32 v3, v21, v32
	s_nop 0
	v_mul_f32_e32 v2, v14, v2
	v_mul_f32_e32 v3, v15, v3
	v_cvt_pk_bf16_f32 v182, v2, v3
	v_mul_f32_e32 v3, v22, v32
; __device__ __forceinline__ unsigned pk2(float lo, float hi) { return pg8::cvt_pk_bf16(lo, hi); }
; template <int MODE> ...
;     ...
;             for (int dt = 0; dt < 2; ++dt)
; #pragma unroll
;                 for (int ii = 0; ii < 4; ++ii) { const int d0 = head * 64 + 32 * dt + 8 * ii + 4 * h; const f32x4 gv = *(const f32x4*)(gain + d0);
;                     u32x2 w; w.x = pk2(o[dt][4 * ii] * rr * gv[0], o[dt][4 * ii + 1] * rr * gv[1]); w.y = pk2(o[dt][4 * ii + 2] * rr * gv[2], o[dt][4 * ii + 3] * rr * gv[3]);
;                     *(u32x2*)(Y + row * DM + d0) = w; }
	v_mul_f32_e32 v3, v16, v3
	v_mul_f32_e32 v14, v23, v32
	v_mul_f32_e32 v14, v17, v14
	v_cvt_pk_bf16_f32 v183, v3, v14
	s_nop 1
	v_permlane32_swap_b32_e32 v180, v182
	v_permlane32_swap_b32_e32 v181, v183
	v_lshl_add_u64 v[226:227], v[0:1], 0, v[232:233]
	global_store_dwordx4 v[226:227], v[180:183], off offset:0
	v_mov_b32_e32 v14, v200
	v_mov_b32_e32 v15, v201
	v_mov_b32_e32 v16, v202
	v_mov_b32_e32 v17, v203
	v_mul_f32_e32 v2, v36, v32
	v_mul_f32_e32 v3, v33, v32
	s_nop 0
	v_mul_f32_e32 v2, v14, v2
	v_mul_f32_e32 v3, v15, v3
	v_cvt_pk_bf16_f32 v228, v2, v3
	v_mul_f32_e32 v3, v25, v32
	v_mul_f32_e32 v3, v16, v3
	v_mul_f32_e32 v14, v24, v32
	v_mul_f32_e32 v14, v17, v14
	v_cvt_pk_bf16_f32 v229, v3, v14
	s_nop 0
	v_mov_b32_e32 v14, v204
	v_mov_b32_e32 v15, v205
	v_mov_b32_e32 v16, v206
	v_mov_b32_e32 v17, v207
	v_mul_f32_e32 v2, v37, v32
	v_mul_f32_e32 v3, v28, v32
	s_nop 0
	v_mul_f32_e32 v2, v14, v2
	v_mul_f32_e32 v3, v15, v3
	v_cvt_pk_bf16_f32 v230, v2, v3
	v_mul_f32_e32 v3, v27, v32
	v_mul_f32_e32 v3, v16, v3
	v_mul_f32_e32 v14, v26, v32
	v_mul_f32_e32 v14, v17, v14
	v_cvt_pk_bf16_f32 v231, v3, v14
	s_nop 1
	v_permlane32_swap_b32_e32 v228, v230
	v_permlane32_swap_b32_e32 v229, v231
	v_lshl_add_u64 v[226:227], v[0:1], 0, v[232:233]
	global_store_dwordx4 v[226:227], v[228:231], off offset:32
	v_mov_b32_e32 v14, v208
	v_mov_b32_e32 v15, v209
	v_mov_b32_e32 v16, v210
	v_mov_b32_e32 v17, v211
	v_mul_f32_e32 v2, v39, v32
	v_mul_f32_e32 v3, v31, v32
	s_nop 0
	v_mul_f32_e32 v2, v14, v2
	v_mul_f32_e32 v3, v15, v3
	v_cvt_pk_bf16_f32 v180, v2, v3
	v_mul_f32_e32 v3, v30, v32
	v_mul_f32_e32 v3, v16, v3
	v_mul_f32_e32 v14, v29, v32
	v_mul_f32_e32 v14, v17, v14
	v_cvt_pk_bf16_f32 v181, v3, v14
	s_nop 0
	v_mov_b32_e32 v14, v212
	v_mov_b32_e32 v15, v213
	v_mov_b32_e32 v16, v214
	v_mov_b32_e32 v17, v215
	v_mul_f32_e32 v2, v41, v32
	v_mul_f32_e32 v3, v40, v32
	s_nop 0
	v_mul_f32_e32 v2, v14, v2
	v_mul_f32_e32 v3, v15, v3
	v_cvt_pk_bf16_f32 v182, v2, v3
	v_mul_f32_e32 v3, v4, v32
	v_mul_f32_e32 v3, v16, v3
	v_mul_f32_e32 v4, v5, v32
	v_mul_f32_e32 v4, v17, v4
	v_cvt_pk_bf16_f32 v183, v3, v4
	s_nop 1
	v_permlane32_swap_b32_e32 v180, v182
	v_permlane32_swap_b32_e32 v181, v183
	v_lshl_add_u64 v[226:227], v[0:1], 0, v[232:233]
	global_store_dwordx4 v[226:227], v[180:183], off offset:64
	v_mov_b32_e32 v2, v216
	v_mov_b32_e32 v3, v217
	v_mov_b32_e32 v4, v218
	v_mov_b32_e32 v5, v219
	s_nop 0
	v_mul_f32_e32 v2, v2, v8
	v_mul_f32_e32 v8, v9, v32
	v_mul_f32_e32 v3, v3, v8
	v_cvt_pk_bf16_f32 v228, v2, v3
	v_mul_f32_e32 v3, v6, v32
	v_mul_f32_e32 v3, v4, v3
	v_mul_f32_e32 v4, v7, v32
	v_mul_f32_e32 v4, v5, v4
	v_cvt_pk_bf16_f32 v229, v3, v4
	s_nop 0
	v_mov_b32_e32 v2, v220
	v_mov_b32_e32 v3, v221
	v_mov_b32_e32 v4, v222
	v_mov_b32_e32 v5, v223
	v_mul_f32_e32 v6, v10, v32
	s_nop 0
	v_mul_f32_e32 v2, v2, v6
	v_mul_f32_e32 v6, v11, v32
	v_mul_f32_e32 v3, v3, v6
	v_cvt_pk_bf16_f32 v230, v2, v3
	v_mul_f32_e32 v3, v12, v32
	v_mul_f32_e32 v3, v4, v3
	v_mul_f32_e32 v4, v13, v32
	v_mul_f32_e32 v4, v5, v4
	v_cvt_pk_bf16_f32 v231, v3, v4
	s_nop 1
	v_permlane32_swap_b32_e32 v228, v230
	v_permlane32_swap_b32_e32 v229, v231
	v_lshl_add_u64 v[226:227], v[0:1], 0, v[232:233]
	global_store_dwordx4 v[226:227], v[228:231], off offset:96
	s_cbranch_scc1 .LBB0_627
; #define LAS __attribute__((address_space(3)))
; template <int MODE> ...
;     const int r = lane & 31, h = lane >> 5, li = lane & 15, gg = (lane >> 4) & 1;
;     const size_t seqrow0 = (size_t)b * SEQL + res;
;     const int q0 = 32 * qt;
;     const size_t rstride = (size_t)dil * PW;
;     bf16x8 qf[4];
;     { const bf16_t* qp = PR + (seqrow0 + (size_t)(q0 + r) * dil) * PW + PC_QA + head * 64 + 8 * h;
; #pragma unroll
;       for (int s = 0; s < 4; ++s) qf[s] = *(const bf16x8*)(qp + 16 * s); }
;     f32x16 o[2];
; #pragma unroll
;     for (int dt = 0; dt < 2; ++dt)
; #pragma unroll
;         for (int i = 0; i < 16; ++i) o[dt][i] = 0.f;
;     float l = 0.f;
;     const float slope = exp2f(-(float)(head + 1)) * LOG2E * (float)dil;
;     const LAS unsigned char* trb = vl + (4 * h + (li >> 2)) * VROW + (16 * gg + 4 * (li & 3)) * 2;
;     const int first = (q0 >= 128) ? 0 : ((128 - q0) >> 5);
;     const size_t prow = (seqrow0 + (size_t)(q0 - 128 + 32 * first + (lane >> 3)) * dil) * PW + head * 64 + 8 * (lane & 7);
;     const bf16_t* kp = PR + prow + PC_KA; const bf16_t* vp = PR + prow + PC_VA;
;     LAS unsigned char* kl = vl + 4608;
;     const int stoff = (lane >> 3) * VROW + 16 * (lane & 7);
;     u32x4 kn[4], vn[4];
; #pragma unroll
;     for (int i = 0; i < 4; ++i) { kn[i] = *(const u32x4*)(kp + (size_t)(8 * i) * rstride); vn[i] = *(const u32x4*)(vp + (size_t)(8 * i) * rstride); }
;     const int rr = r - 4 * h;
; __global__ void __launch_bounds__(512, 2) mega(Args a) {
;     ...
;         for (int task = bx * 8 + wave; task < 8192; task += G * 8) { const int bh = task >> 6, wq = task & 63;
;             attn_task<1>(WSP(bf16_t, WS_H), bh >> 3, bh & 7, 0, 1, wq, vl, nullptr, nullptr, WSP(bf16_t, WS_P4), WSP(bf16_t, WS_P16), WSP(float, WS_L4), WSP(float, WS_L16), a.in[I_AG], (bf16_t*)a.out, lane); }
.LBB0_618:
	s_bfe_u32 s91, s33, 0x60006
	s_bfe_u32 s0, s33, 0x30003
	s_bfe_u32 s98, s33, 0x1000c
	s_lshl_b32 s98, s98, 3
	s_or_b32 s0, s0, s98
	s_ashr_i32 s1, s0, 31
	s_lshl_b32 s86, s91, 5
	s_lshl_b64 s[0:1], s[0:1], 11
	v_or_b32_e32 v0, s86, v99
	v_or_b32_e32 v106, s0, v0
	s_movk_i32 s78, 0x1c00
	s_and_b32 s90, s33, 7
	v_mad_u64_u32 v[0:1], s[2:3], v106, s78, v[102:103]
	s_add_i32 s2, s90, 1
	s_nop 0
	v_cvt_f32_ubyte0_e32 v4, s2
	s_mov_b32 s2, 0x42fc0000
	s_lshl_b32 s83, s90, 6
	s_lshl_b32 s76, s90, 7
	v_cmp_lt_f32_e32 vcc, s2, v4
	s_and_b64 s[2:3], vcc, exec
	s_cselect_b32 s87, 0xffffffc0, 0
	s_sub_i32 s2, 0x80, s86
	s_ashr_i32 s2, s2, 5
	s_cmp_lt_u32 s91, 4
	v_mad_i32_i24 v1, s1, v128, v1
	s_cselect_b32 s91, s2, 0
	v_lshl_add_u64 v[0:1], v[0:1], 0, s[76:77]
	s_lshl_b32 s88, s91, 5
	v_lshl_add_u64 v[0:1], v[0:1], 0, v[104:105]
	s_add_i32 s2, s88, s86
	global_load_dwordx4 v[48:51], v[0:1], off
	global_load_dwordx4 v[52:55], v[0:1], off offset:32
	global_load_dwordx4 v[56:59], v[0:1], off offset:64
	global_load_dwordx4 v[60:63], v[0:1], off offset:96
	v_add_u32_e32 v0, s2, v126
	v_ashrrev_i32_e32 v1, 31, v0
	v_lshl_add_u64 v[0:1], s[0:1], 0, v[0:1]
	v_mad_u64_u32 v[2:3], s[2:3], v0, s78, v[100:101]
	v_mad_i32_i24 v3, v1, s78, v3
	v_lshl_add_u64 v[0:1], v[2:3], 0, s[76:77]
	s_mov_b32 s0, 0x2a000
	v_cndmask_b32_e32 v5, 0, v129, vcc
	v_add_co_u32_e32 v2, vcc, s0, v0
	s_mov_b32 s0, 0x1c000
	s_nop 0
	v_addc_co_u32_e32 v3, vcc, 0, v1, vcc
	global_load_dwordx4 v[92:95], v[2:3], off offset:2048
	global_load_dwordx4 v[88:91], v[2:3], off offset:1024
	v_add_co_u32_e32 v2, vcc, s0, v0
	s_mov_b32 s0, 0xe000
	s_nop 0
	v_addc_co_u32_e32 v3, vcc, 0, v1, vcc
	global_load_dwordx4 v[84:87], v[2:3], off offset:2048
	global_load_dwordx4 v[80:83], v[2:3], off offset:1024
	v_add_co_u32_e32 v2, vcc, s0, v0
	v_mov_b32_e32 v107, s1
	s_nop 0
	v_addc_co_u32_e32 v3, vcc, 0, v1, vcc
	global_load_dwordx4 v[76:79], v[2:3], off offset:2048
	global_load_dwordx4 v[72:75], v[2:3], off offset:1024
	global_load_dwordx4 v[68:71], v[0:1], off offset:2048
	global_load_dwordx4 v[64:67], v[0:1], off offset:1024
	v_lshlrev_b64 v[178:179], 5, v[106:107]
	v_lshl_or_b32 v178, s90, 2, v178
	v_lshl_add_u64 v[180:181], s[92:93], 0, v[178:179]
	global_load_dword v177, v[180:181], off
	v_lshl_add_u64 v[182:183], s[94:95], 0, v[178:179]
	global_load_dword v184, v[182:183], off
	v_lshlrev_b32_e32 v176, 9, v106
	v_or3_b32 v176, v176, v98, s83
	v_lshlrev_b32_e32 v176, 1, v176
	v_and_b32_e32 v232, 32, v135
	v_lshrrev_b32_e32 v232, 2, v232
	v_mov_b32_e32 v233, 0
	v_add_u32_e32 v176, v176, v232
	v_or_b32_e32 v225, s83, v98
	v_lshlrev_b32_e32 v225, 2, v225
	v_readlane_b32 s100, v235, 24
	v_readlane_b32 s101, v235, 25
	global_load_dwordx4 v[144:147], v176, s[72:73] offset:0
	global_load_dwordx4 v[148:151], v176, s[72:73] offset:32
	global_load_dwordx4 v[152:155], v176, s[72:73] offset:64
	global_load_dwordx4 v[156:159], v176, s[72:73] offset:96
	global_load_dwordx4 v[160:163], v176, s[74:75] offset:0
	global_load_dwordx4 v[164:167], v176, s[74:75] offset:32
	global_load_dwordx4 v[168:171], v176, s[74:75] offset:64
	global_load_dwordx4 v[172:175], v176, s[74:75] offset:96
	s_nop 1
	global_load_dwordx4 v[192:195], v225, s[100:101] offset:0
	global_load_dwordx4 v[196:199], v225, s[100:101] offset:32
	global_load_dwordx4 v[200:203], v225, s[100:101] offset:64
	global_load_dwordx4 v[204:207], v225, s[100:101] offset:96
	global_load_dwordx4 v[208:211], v225, s[100:101] offset:128
	global_load_dwordx4 v[212:215], v225, s[100:101] offset:160
	global_load_dwordx4 v[216:219], v225, s[100:101] offset:192
	global_load_dwordx4 v[220:223], v225, s[100:101] offset:224
	v_sub_f32_e32 v2, v5, v4
	v_exp_f32_e32 v2, v2
	s_mov_b64 s[0:1], 0x800
	v_lshl_add_u64 v[112:113], v[0:1], 0, s[0:1]
	s_mov_b64 s[0:1], 0x400
	v_ldexp_f32 v2, v2, s87
	v_lshl_add_u64 v[118:119], v[0:1], 0, s[0:1]
	s_mov_b32 s0, 2.0
	v_mul_f32_e32 v96, 0x3fb8aa3b, v2
	s_mov_b32 s1, 0x40400000
	v_pk_mul_f32 v[108:109], v[96:97], s[0:1] op_sel_hi:[0,1]
	s_mov_b32 s0, 0x41000000
	s_mov_b32 s1, 0x41100000
	v_pk_mul_f32 v[110:111], v[96:97], s[0:1] op_sel_hi:[0,1]
	s_mov_b32 s0, 0x41200000
	s_mov_b32 s1, 0x41300000
	v_pk_mul_f32 v[114:115], v[96:97], s[0:1] op_sel_hi:[0,1]
	s_mov_b32 s0, 0x41800000
	s_mov_b32 s1, 0x41880000
	v_pk_mul_f32 v[116:117], v[96:97], s[0:1] op_sel_hi:[0,1]
	s_mov_b32 s0, 0x41900000
	s_mov_b32 s1, 0x41980000
	v_pk_mul_f32 v[120:121], v[96:97], s[0:1] op_sel_hi:[0,1]
	s_mov_b32 s0, 0x41c00000
	s_mov_b32 s1, 0x41c80000
	v_mul_f32_e32 v136, 0, v96
	v_pk_mul_f32 v[122:123], v[96:97], s[0:1] op_sel_hi:[0,1]
	v_pk_mul_f32 v[124:125], v[96:97], s[96:97] op_sel_hi:[0,1]
	v_subrev_u32_e32 v137, s88, v127
	v_mov_b32_e32 v138, 0
	v_mov_b32_e32 v16, 0
	v_mov_b32_e32 v17, v97
	v_mov_b32_e32 v18, v97
	v_mov_b32_e32 v19, v97
	v_mov_b32_e32 v20, v97
	v_mov_b32_e32 v21, v97
	v_mov_b32_e32 v22, v97
	v_mov_b32_e32 v23, v97
	v_mov_b32_e32 v24, v97
	v_mov_b32_e32 v25, v97
	v_mov_b32_e32 v26, v97
	v_mov_b32_e32 v27, v97
	v_mov_b32_e32 v28, v97
	v_mov_b32_e32 v29, v97
	v_mov_b32_e32 v30, v97
	v_mov_b32_e32 v31, v97
	v_mov_b32_e32 v0, 0
	v_mov_b32_e32 v1, v97
	v_mov_b32_e32 v2, v97
	v_mov_b32_e32 v3, v97
	v_mov_b32_e32 v4, v97
	v_mov_b32_e32 v5, v97
	v_mov_b32_e32 v6, v97
	v_mov_b32_e32 v7, v97
	v_mov_b32_e32 v8, v97
	v_mov_b32_e32 v9, v97
	v_mov_b32_e32 v10, v97
	v_mov_b32_e32 v11, v97
	v_mov_b32_e32 v12, v97
	v_mov_b32_e32 v13, v97
	v_mov_b32_e32 v14, v97
	v_mov_b32_e32 v15, v97
